# f1-plus-64bit-accumulator-clears
# speedup vs baseline: 1.0032x; 1.0010x over previous
;     __device__ bool next(int i, Unit& u) const { const int r = i / nN, pn = i - r * nN, pm = c + r * G; if (pm >= nM) return false; u.pm = pm; u.pn = pn; return true; }
; template <class Epi, class Sched>
; __device__ __forceinline__ void gemm_phase(LAS unsigned char* lds, Gemm g, Sched S, const Epi& E) {
;     ...
;         const bool has_next = S.next(ui + 1, nxt);
;         const char* nA = has_next ? baseA(g, nxt) : cA; const char* nB = has_next ? baseB(g, nxt) : cB;
;         for (int t = 0; t < nt; t += 2) {
;             const bool last = (t == nt - 2);
;             const char* a1 = cA + (size_t)(t + 1) * kstep;
;             const char* a2 = last ? nA : cA + (size_t)(t + 2) * kstep; const char* b2 = last ? nB : cB + (size_t)(t + 2) * kstep;
;     ...
; #pragma unroll
;         for (int a = 0; a < 2; ++a)
; #pragma unroll
;             for (int b = 0; b < 2; ++b)
; #pragma unroll
;                 for (int m = 0; m < 4; ++m)
; #pragma unroll
;                     for (int n = 0; n < 2; ++n) acc[a][b][m][n] = (f32x4){0.f, 0.f, 0.f, 0.f};
.LBB0_253:
	s_ashr_i32 s17, s16, 31
	s_lshl_b64 s[18:19], s[16:17], 19
	s_add_u32 s18, s8, s18
	s_addc_u32 s19, s9, s19
	s_and_b64 s[20:21], s[0:1], exec
	s_cselect_b32 s17, s19, s27
	s_cselect_b32 s57, s18, s26
	s_ashr_i32 s15, s14, 31
	s_lshl_b64 s[20:21], s[14:15], 19
	s_add_u32 s20, s4, s20
	s_addc_u32 s21, s5, s21
	s_and_b64 s[28:29], s[0:1], exec
	s_cselect_b32 s15, s21, s25
	s_cselect_b32 s66, s20, s24
	s_add_u32 s67, s24, 0x100
	s_addc_u32 s74, s25, 0
	s_add_u32 s24, s26, 0x40080
	s_addc_u32 s25, s27, 0
	s_mov_b32 s75, -2
	v_mov_b64_e32 v[2:3], 0
	v_mov_b64_e32 v[4:5], 0
	v_mov_b64_e32 v[6:7], 0
	v_mov_b64_e32 v[8:9], 0
	v_mov_b64_e32 v[10:11], 0
	v_mov_b64_e32 v[12:13], 0
	v_mov_b64_e32 v[14:15], 0
	v_mov_b64_e32 v[16:17], 0
	v_mov_b64_e32 v[18:19], 0
	v_mov_b64_e32 v[20:21], 0
	v_mov_b64_e32 v[22:23], 0
	v_mov_b64_e32 v[24:25], 0
	v_mov_b64_e32 v[26:27], 0
	v_mov_b64_e32 v[28:29], 0
	v_mov_b64_e32 v[30:31], 0
	v_mov_b64_e32 v[32:33], 0
	v_mov_b64_e32 v[34:35], 0
	v_mov_b64_e32 v[36:37], 0
	v_mov_b64_e32 v[38:39], 0
	v_mov_b64_e32 v[40:41], 0
	v_mov_b64_e32 v[42:43], 0
	v_mov_b64_e32 v[44:45], 0
	v_mov_b64_e32 v[46:47], 0
	v_mov_b64_e32 v[48:49], 0
	v_mov_b64_e32 v[50:51], 0
	v_mov_b64_e32 v[52:53], 0
	v_mov_b64_e32 v[54:55], 0
	v_mov_b64_e32 v[56:57], 0
	v_mov_b64_e32 v[58:59], 0
	v_mov_b64_e32 v[60:61], 0
	v_mov_b64_e32 v[62:63], 0
	v_mov_b64_e32 v[64:65], 0
	v_mov_b64_e32 v[66:67], 0
	v_mov_b64_e32 v[68:69], 0
	v_mov_b64_e32 v[70:71], 0
	v_mov_b64_e32 v[72:73], 0
	v_mov_b64_e32 v[74:75], 0
	v_mov_b64_e32 v[76:77], 0
	v_mov_b64_e32 v[78:79], 0
	v_mov_b64_e32 v[80:81], 0
	v_mov_b64_e32 v[82:83], 0
	v_mov_b64_e32 v[84:85], 0
	v_mov_b64_e32 v[86:87], 0
	v_mov_b64_e32 v[88:89], 0
	v_mov_b64_e32 v[90:91], 0
	v_mov_b64_e32 v[92:93], 0
	v_mov_b64_e32 v[94:95], 0
	v_mov_b64_e32 v[96:97], 0
	v_mov_b64_e32 v[98:99], 0
	v_mov_b64_e32 v[100:101], 0
	v_mov_b64_e32 v[102:103], 0
	v_mov_b64_e32 v[104:105], 0
	v_mov_b64_e32 v[106:107], 0
	v_mov_b64_e32 v[108:109], 0
	v_mov_b64_e32 v[110:111], 0
	v_mov_b64_e32 v[112:113], 0
	v_mov_b64_e32 v[114:115], 0
	v_mov_b64_e32 v[116:117], 0
	v_mov_b64_e32 v[118:119], 0
	v_mov_b64_e32 v[120:121], 0
	v_mov_b64_e32 v[138:139], 0
	v_mov_b64_e32 v[140:141], 0
	v_mov_b64_e32 v[142:143], 0
	v_mov_b64_e32 v[144:145], 0

;     __device__ bool next(int i, Unit& u) const { const int r = i / nN, pn = i - r * nN, pm = c + r * G; if (pm >= nM) return false; u.pm = pm; u.pn = pn; return true; }
; template <class Epi, class Sched>
; __device__ __forceinline__ void gemm_phase(LAS unsigned char* lds, Gemm g, Sched S, const Epi& E) {
;     ...
;         const bool has_next = S.next(ui + 1, nxt);
;         const char* nA = has_next ? baseA(g, nxt) : cA; const char* nB = has_next ? baseB(g, nxt) : cB;
;         for (int t = 0; t < nt; t += 2) {
;             const bool last = (t == nt - 2);
;             const char* a1 = cA + (size_t)(t + 1) * kstep;
;             const char* a2 = last ? nA : cA + (size_t)(t + 2) * kstep; const char* b2 = last ? nB : cB + (size_t)(t + 2) * kstep;
;     ...
; #pragma unroll
;         for (int a = 0; a < 2; ++a)
; #pragma unroll
;             for (int b = 0; b < 2; ++b)
; #pragma unroll
;                 for (int m = 0; m < 4; ++m)
; #pragma unroll
;                     for (int n = 0; n < 2; ++n) acc[a][b][m][n] = (f32x4){0.f, 0.f, 0.f, 0.f};
.LBB0_294:
	s_ashr_i32 s25, s24, 31
	s_lshl_b64 s[28:29], s[24:25], 19
	s_add_u32 s28, s8, s28
	s_addc_u32 s29, s9, s29
	s_and_b64 s[4:5], s[4:5], exec
	s_cselect_b32 s23, s29, s31
	s_cselect_b32 s25, s28, s30
	s_add_u32 s75, s34, 0x100
	s_addc_u32 vcc_lo, s35, 0
	s_add_u32 s4, s30, 0x40080
	s_addc_u32 s5, s31, 0
	s_mov_b32 vcc_hi, -2
	v_mov_b64_e32 v[2:3], 0
	v_mov_b64_e32 v[4:5], 0
	v_mov_b64_e32 v[6:7], 0
	v_mov_b64_e32 v[8:9], 0
	v_mov_b64_e32 v[10:11], 0
	v_mov_b64_e32 v[12:13], 0
	v_mov_b64_e32 v[14:15], 0
	v_mov_b64_e32 v[16:17], 0
	v_mov_b64_e32 v[18:19], 0
	v_mov_b64_e32 v[20:21], 0
	v_mov_b64_e32 v[22:23], 0
	v_mov_b64_e32 v[24:25], 0
	v_mov_b64_e32 v[26:27], 0
	v_mov_b64_e32 v[28:29], 0
	v_mov_b64_e32 v[30:31], 0
	v_mov_b64_e32 v[32:33], 0
	v_mov_b64_e32 v[34:35], 0
	v_mov_b64_e32 v[36:37], 0
	v_mov_b64_e32 v[38:39], 0
	v_mov_b64_e32 v[40:41], 0
	v_mov_b64_e32 v[42:43], 0
	v_mov_b64_e32 v[44:45], 0
	v_mov_b64_e32 v[46:47], 0
	v_mov_b64_e32 v[48:49], 0
	v_mov_b64_e32 v[50:51], 0
	v_mov_b64_e32 v[52:53], 0
	v_mov_b64_e32 v[54:55], 0
	v_mov_b64_e32 v[56:57], 0
	v_mov_b64_e32 v[58:59], 0
	v_mov_b64_e32 v[60:61], 0
	v_mov_b64_e32 v[62:63], 0
	v_mov_b64_e32 v[64:65], 0
	v_mov_b64_e32 v[66:67], 0
	v_mov_b64_e32 v[68:69], 0
	v_mov_b64_e32 v[70:71], 0
	v_mov_b64_e32 v[72:73], 0
	v_mov_b64_e32 v[74:75], 0
	v_mov_b64_e32 v[76:77], 0
	v_mov_b64_e32 v[78:79], 0
	v_mov_b64_e32 v[80:81], 0
	v_mov_b64_e32 v[82:83], 0
	v_mov_b64_e32 v[84:85], 0
	v_mov_b64_e32 v[86:87], 0
	v_mov_b64_e32 v[88:89], 0
	v_mov_b64_e32 v[90:91], 0
	v_mov_b64_e32 v[92:93], 0
	v_mov_b64_e32 v[94:95], 0
	v_mov_b64_e32 v[96:97], 0
	v_mov_b64_e32 v[98:99], 0
	v_mov_b64_e32 v[100:101], 0
	v_mov_b64_e32 v[102:103], 0
	v_mov_b64_e32 v[104:105], 0
	v_mov_b64_e32 v[106:107], 0
	v_mov_b64_e32 v[108:109], 0
	v_mov_b64_e32 v[110:111], 0
	v_mov_b64_e32 v[112:113], 0
	v_mov_b64_e32 v[114:115], 0
	v_mov_b64_e32 v[116:117], 0
	v_mov_b64_e32 v[118:119], 0
	v_mov_b64_e32 v[120:121], 0
	v_mov_b64_e32 v[122:123], 0
	v_mov_b64_e32 v[124:125], 0
	v_mov_b64_e32 v[126:127], 0
	v_mov_b64_e32 v[128:129], 0

;     __device__ bool next(int i, Unit& u) const { const int r = i / nN, pn = i - r * nN, pm = c + r * G; if (pm >= nM) return false; u.pm = pm; u.pn = pn; return true; }
; template <class Epi, class Sched>
; __device__ __forceinline__ void gemm_phase(LAS unsigned char* lds, Gemm g, Sched S, const Epi& E) {
;     ...
;         const bool has_next = S.next(ui + 1, nxt);
;         const char* nA = has_next ? baseA(g, nxt) : cA; const char* nB = has_next ? baseB(g, nxt) : cB;
;         for (int t = 0; t < nt; t += 2) {
;             const bool last = (t == nt - 2);
;             const char* a1 = cA + (size_t)(t + 1) * kstep;
;             const char* a2 = last ? nA : cA + (size_t)(t + 2) * kstep; const char* b2 = last ? nB : cB + (size_t)(t + 2) * kstep;
;     ...
; #pragma unroll
;         for (int a = 0; a < 2; ++a)
; #pragma unroll
;             for (int b = 0; b < 2; ++b)
; #pragma unroll
;                 for (int m = 0; m < 4; ++m)
; #pragma unroll
;                     for (int n = 0; n < 2; ++n) acc[a][b][m][n] = (f32x4){0.f, 0.f, 0.f, 0.f};
.LBB0_529:
	s_ashr_i32 s17, s16, 31
	s_lshl_b64 s[18:19], s[16:17], 19
	s_add_u32 s18, s8, s18
	s_addc_u32 s19, s9, s19
	s_and_b64 s[20:21], s[0:1], exec
	s_cselect_b32 s5, s19, s27
	s_cselect_b32 s17, s18, s26
	s_ashr_i32 s15, s14, 31
	s_lshl_b64 s[20:21], s[14:15], 19
	s_add_u32 s20, s6, s20
	s_addc_u32 s21, s7, s21
	s_and_b64 s[28:29], s[0:1], exec
	s_cselect_b32 s15, s21, s25
	s_cselect_b32 s47, s20, s24
	s_add_u32 s48, s24, 0x100
	s_addc_u32 s49, s25, 0
	s_add_u32 s24, s26, 0x40080
	s_addc_u32 s25, s27, 0
	s_mov_b32 s50, -2
	v_mov_b64_e32 v[2:3], 0
	v_mov_b64_e32 v[4:5], 0
	v_mov_b64_e32 v[6:7], 0
	v_mov_b64_e32 v[8:9], 0
	v_mov_b64_e32 v[10:11], 0
	v_mov_b64_e32 v[12:13], 0
	v_mov_b64_e32 v[14:15], 0
	v_mov_b64_e32 v[16:17], 0
	v_mov_b64_e32 v[18:19], 0
	v_mov_b64_e32 v[20:21], 0
	v_mov_b64_e32 v[22:23], 0
	v_mov_b64_e32 v[24:25], 0
	v_mov_b64_e32 v[26:27], 0
	v_mov_b64_e32 v[28:29], 0
	v_mov_b64_e32 v[30:31], 0
	v_mov_b64_e32 v[32:33], 0
	v_mov_b64_e32 v[34:35], 0
	v_mov_b64_e32 v[36:37], 0
	v_mov_b64_e32 v[38:39], 0
	v_mov_b64_e32 v[40:41], 0
	v_mov_b64_e32 v[42:43], 0
	v_mov_b64_e32 v[44:45], 0
	v_mov_b64_e32 v[46:47], 0
	v_mov_b64_e32 v[48:49], 0
	v_mov_b64_e32 v[50:51], 0
	v_mov_b64_e32 v[52:53], 0
	v_mov_b64_e32 v[54:55], 0
	v_mov_b64_e32 v[56:57], 0
	v_mov_b64_e32 v[58:59], 0
	v_mov_b64_e32 v[60:61], 0
	v_mov_b64_e32 v[62:63], 0
	v_mov_b64_e32 v[64:65], 0
	v_mov_b64_e32 v[66:67], 0
	v_mov_b64_e32 v[68:69], 0
	v_mov_b64_e32 v[70:71], 0
	v_mov_b64_e32 v[72:73], 0
	v_mov_b64_e32 v[74:75], 0
	v_mov_b64_e32 v[76:77], 0
	v_mov_b64_e32 v[78:79], 0
	v_mov_b64_e32 v[80:81], 0
	v_mov_b64_e32 v[82:83], 0
	v_mov_b64_e32 v[84:85], 0
	v_mov_b64_e32 v[86:87], 0
	v_mov_b64_e32 v[88:89], 0
	v_mov_b64_e32 v[90:91], 0
	v_mov_b64_e32 v[92:93], 0
	v_mov_b64_e32 v[94:95], 0
	v_mov_b64_e32 v[96:97], 0
	v_mov_b64_e32 v[98:99], 0
	v_mov_b64_e32 v[100:101], 0
	v_mov_b64_e32 v[102:103], 0
	v_mov_b64_e32 v[104:105], 0
	v_mov_b64_e32 v[106:107], 0
	v_mov_b64_e32 v[108:109], 0
	v_mov_b64_e32 v[110:111], 0
	v_mov_b64_e32 v[112:113], 0
	v_mov_b64_e32 v[114:115], 0
	v_mov_b64_e32 v[116:117], 0
	v_mov_b64_e32 v[118:119], 0
	v_mov_b64_e32 v[120:121], 0
	v_mov_b64_e32 v[122:123], 0
	v_mov_b64_e32 v[124:125], 0
	v_mov_b64_e32 v[126:127], 0
	v_mov_b64_e32 v[128:129], 0

;     __device__ bool next(int i, Unit& u) const { const int r = i / nN, pn = i - r * nN, pm = c + r * G; if (pm >= nM) return false; u.pm = pm; u.pn = pn; return true; }
; template <class Epi, class Sched>
; __device__ __forceinline__ void gemm_phase(LAS unsigned char* lds, Gemm g, Sched S, const Epi& E) {
;     ...
;         const bool has_next = S.next(ui + 1, nxt);
;         const char* nA = has_next ? baseA(g, nxt) : cA; const char* nB = has_next ? baseB(g, nxt) : cB;
;         for (int t = 0; t < nt; t += 2) {
;             const bool last = (t == nt - 2);
;             const char* a1 = cA + (size_t)(t + 1) * kstep;
;             const char* a2 = last ? nA : cA + (size_t)(t + 2) * kstep; const char* b2 = last ? nB : cB + (size_t)(t + 2) * kstep;
;     ...
; #pragma unroll
;         for (int a = 0; a < 2; ++a)
; #pragma unroll
;             for (int b = 0; b < 2; ++b)
; #pragma unroll
;                 for (int m = 0; m < 4; ++m)
; #pragma unroll
;                     for (int n = 0; n < 2; ++n) acc[a][b][m][n] = (f32x4){0.f, 0.f, 0.f, 0.f};
.LBB0_971:
	s_add_i32 s40, s40, 1
	s_mov_b64 s[0:1], s[8:9]
	s_lshr_b32 s8, s40, 2
	s_mul_i32 s8, s8, s28
	s_mov_b64 s[22:23], s[18:19]
	s_mov_b32 s19, s41
	s_mov_b32 s42, s41
	s_add_i32 s41, s8, s6
	s_cmpk_lt_i32 s41, 0x100
	s_mov_b32 s18, s39
	s_mov_b32 s43, s39
	s_cselect_b64 s[20:21], -1, 0
	s_and_b32 s39, s40, 3
	s_and_b64 s[8:9], s[20:21], exec
	s_cselect_b32 s8, s41, s19
	s_cselect_b32 s18, s39, s18
	s_ashr_i32 s9, s8, 31
	s_lshl_b64 s[8:9], s[8:9], 19
	s_mov_b64 s[24:25], s[58:59]
	s_add_u32 s8, s24, s8
	s_addc_u32 s9, s25, s9
	s_and_b64 s[24:25], s[20:21], exec
	s_cselect_b32 s44, s9, s1
	s_cselect_b32 s45, s8, s0
	s_ashr_i32 s19, s18, 31
	s_lshl_b64 s[18:19], s[18:19], 19
	s_add_u32 s18, s4, s18
	s_addc_u32 s19, s5, s19
	s_and_b64 s[24:25], s[20:21], exec
	s_cselect_b32 s46, s19, s23
	s_cselect_b32 s47, s18, s22
	s_add_u32 s48, s22, 0x100
	s_addc_u32 s49, s23, 0
	s_add_u32 s0, s0, 0x40080
	s_addc_u32 s1, s1, 0
	s_mov_b32 s50, -2
	v_mov_b64_e32 v[2:3], 0
	v_mov_b64_e32 v[4:5], 0
	v_mov_b64_e32 v[6:7], 0
	v_mov_b64_e32 v[8:9], 0
	v_mov_b64_e32 v[10:11], 0
	v_mov_b64_e32 v[12:13], 0
	v_mov_b64_e32 v[14:15], 0
	v_mov_b64_e32 v[16:17], 0
	v_mov_b64_e32 v[18:19], 0
	v_mov_b64_e32 v[20:21], 0
	v_mov_b64_e32 v[22:23], 0
	v_mov_b64_e32 v[24:25], 0
	v_mov_b64_e32 v[26:27], 0
	v_mov_b64_e32 v[28:29], 0
	v_mov_b64_e32 v[30:31], 0
	v_mov_b64_e32 v[32:33], 0
	v_mov_b64_e32 v[34:35], 0
	v_mov_b64_e32 v[36:37], 0
	v_mov_b64_e32 v[38:39], 0
	v_mov_b64_e32 v[40:41], 0
	v_mov_b64_e32 v[42:43], 0
	v_mov_b64_e32 v[44:45], 0
	v_mov_b64_e32 v[46:47], 0
	v_mov_b64_e32 v[48:49], 0
	v_mov_b64_e32 v[50:51], 0
	v_mov_b64_e32 v[52:53], 0
	v_mov_b64_e32 v[54:55], 0
	v_mov_b64_e32 v[56:57], 0
	v_mov_b64_e32 v[58:59], 0
	v_mov_b64_e32 v[60:61], 0
	v_mov_b64_e32 v[62:63], 0
	v_mov_b64_e32 v[64:65], 0
	v_mov_b64_e32 v[66:67], 0
	v_mov_b64_e32 v[68:69], 0
	v_mov_b64_e32 v[70:71], 0
	v_mov_b64_e32 v[72:73], 0
	v_mov_b64_e32 v[82:83], 0
	v_mov_b64_e32 v[84:85], 0
	v_mov_b64_e32 v[86:87], 0
	v_mov_b64_e32 v[88:89], 0
	v_mov_b64_e32 v[98:99], 0
	v_mov_b64_e32 v[100:101], 0
	v_mov_b64_e32 v[102:103], 0
	v_mov_b64_e32 v[104:105], 0
	v_mov_b64_e32 v[106:107], 0
	v_mov_b64_e32 v[108:109], 0
	v_mov_b64_e32 v[110:111], 0
	v_mov_b64_e32 v[112:113], 0
	v_mov_b64_e32 v[114:115], 0
	v_mov_b64_e32 v[116:117], 0
	v_mov_b64_e32 v[118:119], 0
	v_mov_b64_e32 v[120:121], 0
	v_mov_b64_e32 v[122:123], 0
	v_mov_b64_e32 v[124:125], 0
	v_mov_b64_e32 v[126:127], 0
	v_mov_b64_e32 v[128:129], 0
	v_mov_b64_e32 v[130:131], 0
	v_mov_b64_e32 v[132:133], 0
	v_mov_b64_e32 v[134:135], 0
	v_mov_b64_e32 v[136:137], 0
	v_mov_b64_e32 v[138:139], 0
	v_mov_b64_e32 v[140:141], 0
	v_mov_b64_e32 v[142:143], 0
	v_mov_b64_e32 v[144:145], 0

;     __device__ bool next(int i, Unit& u) const { const int r = i / nN, pn = i - r * nN, pm = c + r * G; if (pm >= nM) return false; u.pm = pm; u.pn = pn; return true; }
; template <class Epi, class Sched>
; __device__ __forceinline__ void gemm_phase(LAS unsigned char* lds, Gemm g, Sched S, const Epi& E) {
;     ...
;         const bool has_next = S.next(ui + 1, nxt);
;         const char* nA = has_next ? baseA(g, nxt) : cA; const char* nB = has_next ? baseB(g, nxt) : cB;
;         for (int t = 0; t < nt; t += 2) {
;             const bool last = (t == nt - 2);
;             const char* a1 = cA + (size_t)(t + 1) * kstep;
;             const char* a2 = last ? nA : cA + (size_t)(t + 2) * kstep; const char* b2 = last ? nB : cB + (size_t)(t + 2) * kstep;
;     ...
; #pragma unroll
;         for (int a = 0; a < 2; ++a)
; #pragma unroll
;             for (int b = 0; b < 2; ++b)
; #pragma unroll
;                 for (int m = 0; m < 4; ++m)
; #pragma unroll
;                     for (int n = 0; n < 2; ++n) acc[a][b][m][n] = (f32x4){0.f, 0.f, 0.f, 0.f};
.LBB0_1109:
	s_ashr_i32 s17, s16, 31
	s_lshl_b64 s[18:19], s[16:17], 19
	s_add_u32 s18, s4, s18
	s_addc_u32 s19, s5, s19
	s_and_b64 s[20:21], s[0:1], exec
	s_cselect_b32 s17, s19, s27
	s_cselect_b32 s48, s18, s26
	s_ashr_i32 s15, s14, 31
	s_lshl_b64 s[20:21], s[14:15], 19
	s_add_u32 s20, s8, s20
	s_addc_u32 s21, s9, s21
	s_and_b64 s[28:29], s[0:1], exec
	s_cselect_b32 s15, s21, s25
	s_cselect_b32 s49, s20, s24
	s_add_u32 s50, s24, 0x100
	s_addc_u32 s51, s25, 0
	s_add_u32 s24, s26, 0x40080
	s_addc_u32 s25, s27, 0
	s_mov_b32 s52, -2
	v_mov_b64_e32 v[2:3], 0
	v_mov_b64_e32 v[4:5], 0
	v_mov_b64_e32 v[6:7], 0
	v_mov_b64_e32 v[8:9], 0
	v_mov_b64_e32 v[10:11], 0
	v_mov_b64_e32 v[12:13], 0
	v_mov_b64_e32 v[14:15], 0
	v_mov_b64_e32 v[16:17], 0
	v_mov_b64_e32 v[18:19], 0
	v_mov_b64_e32 v[20:21], 0
	v_mov_b64_e32 v[22:23], 0
	v_mov_b64_e32 v[24:25], 0
	v_mov_b64_e32 v[26:27], 0
	v_mov_b64_e32 v[28:29], 0
	v_mov_b64_e32 v[30:31], 0
	v_mov_b64_e32 v[32:33], 0
	v_mov_b64_e32 v[34:35], 0
	v_mov_b64_e32 v[36:37], 0
	v_mov_b64_e32 v[38:39], 0
	v_mov_b64_e32 v[40:41], 0
	v_mov_b64_e32 v[42:43], 0
	v_mov_b64_e32 v[44:45], 0
	v_mov_b64_e32 v[46:47], 0
	v_mov_b64_e32 v[48:49], 0
	v_mov_b64_e32 v[50:51], 0
	v_mov_b64_e32 v[52:53], 0
	v_mov_b64_e32 v[54:55], 0
	v_mov_b64_e32 v[56:57], 0
	v_mov_b64_e32 v[58:59], 0
	v_mov_b64_e32 v[60:61], 0
	v_mov_b64_e32 v[62:63], 0
	v_mov_b64_e32 v[64:65], 0
	v_mov_b64_e32 v[66:67], 0
	v_mov_b64_e32 v[68:69], 0
	v_mov_b64_e32 v[70:71], 0
	v_mov_b64_e32 v[72:73], 0
	v_mov_b64_e32 v[74:75], 0
	v_mov_b64_e32 v[76:77], 0
	v_mov_b64_e32 v[78:79], 0
	v_mov_b64_e32 v[80:81], 0
	v_mov_b64_e32 v[82:83], 0
	v_mov_b64_e32 v[84:85], 0
	v_mov_b64_e32 v[86:87], 0
	v_mov_b64_e32 v[88:89], 0
	v_mov_b64_e32 v[90:91], 0
	v_mov_b64_e32 v[92:93], 0
	v_mov_b64_e32 v[94:95], 0
	v_mov_b64_e32 v[96:97], 0
	v_mov_b64_e32 v[98:99], 0
	v_mov_b64_e32 v[100:101], 0
	v_mov_b64_e32 v[102:103], 0
	v_mov_b64_e32 v[104:105], 0
	v_mov_b64_e32 v[106:107], 0
	v_mov_b64_e32 v[108:109], 0
	v_mov_b64_e32 v[110:111], 0
	v_mov_b64_e32 v[112:113], 0
	v_mov_b64_e32 v[114:115], 0
	v_mov_b64_e32 v[116:117], 0
	v_mov_b64_e32 v[118:119], 0
	v_mov_b64_e32 v[120:121], 0
	v_mov_b64_e32 v[122:123], 0
	v_mov_b64_e32 v[124:125], 0
	v_mov_b64_e32 v[126:127], 0
	v_mov_b64_e32 v[128:129], 0

;     __device__ bool next(int i, Unit& u) const { const int r = i / nN, pn = i - r * nN, pm = c + r * G; if (pm >= nM) return false; u.pm = pm; u.pn = pn; return true; }
; template <class Epi, class Sched>
; __device__ __forceinline__ void gemm_phase(LAS unsigned char* lds, Gemm g, Sched S, const Epi& E) {
;     ...
;         const bool has_next = S.next(ui + 1, nxt);
;         const char* nA = has_next ? baseA(g, nxt) : cA; const char* nB = has_next ? baseB(g, nxt) : cB;
;         for (int t = 0; t < nt; t += 2) {
;             const bool last = (t == nt - 2);
;             const char* a1 = cA + (size_t)(t + 1) * kstep;
;             const char* a2 = last ? nA : cA + (size_t)(t + 2) * kstep; const char* b2 = last ? nB : cB + (size_t)(t + 2) * kstep;
;     ...
; #pragma unroll
;         for (int a = 0; a < 2; ++a)
; #pragma unroll
;             for (int b = 0; b < 2; ++b)
; #pragma unroll
;                 for (int m = 0; m < 4; ++m)
; #pragma unroll
;                     for (int n = 0; n < 2; ++n) acc[a][b][m][n] = (f32x4){0.f, 0.f, 0.f, 0.f};
.LBB0_1179:
	s_ashr_i32 s21, s20, 31
	s_lshl_b64 s[22:23], s[20:21], 21
	s_add_u32 s22, s6, s22
	s_addc_u32 s23, s7, s23
	s_and_b64 s[24:25], s[0:1], exec
	s_cselect_b32 s5, s23, s31
	s_cselect_b32 s21, s22, s30
	s_ashr_i32 s19, s18, 31
	s_lshl_b64 s[24:25], s[18:19], 21
	s_add_u32 s24, s8, s24
	s_addc_u32 s25, s9, s25
	s_and_b64 s[34:35], s[0:1], exec
	s_cselect_b32 s19, s25, s29
	s_cselect_b32 s27, s24, s28
	s_add_u32 s52, s28, 0x100
	s_addc_u32 s53, s29, 0
	s_add_u32 s28, s30, 0x100080
	s_addc_u32 s29, s31, 0
	s_mov_b32 s56, -2
	v_mov_b64_e32 v[2:3], 0
	v_mov_b64_e32 v[4:5], 0
	v_mov_b64_e32 v[6:7], 0
	v_mov_b64_e32 v[8:9], 0
	v_mov_b64_e32 v[10:11], 0
	v_mov_b64_e32 v[12:13], 0
	v_mov_b64_e32 v[14:15], 0
	v_mov_b64_e32 v[16:17], 0
	v_mov_b64_e32 v[18:19], 0
	v_mov_b64_e32 v[20:21], 0
	v_mov_b64_e32 v[22:23], 0
	v_mov_b64_e32 v[24:25], 0
	v_mov_b64_e32 v[26:27], 0
	v_mov_b64_e32 v[28:29], 0
	v_mov_b64_e32 v[30:31], 0
	v_mov_b64_e32 v[32:33], 0
	v_mov_b64_e32 v[34:35], 0
	v_mov_b64_e32 v[36:37], 0
	v_mov_b64_e32 v[38:39], 0
	v_mov_b64_e32 v[40:41], 0
	v_mov_b64_e32 v[42:43], 0
	v_mov_b64_e32 v[44:45], 0
	v_mov_b64_e32 v[46:47], 0
	v_mov_b64_e32 v[48:49], 0
	v_mov_b64_e32 v[50:51], 0
	v_mov_b64_e32 v[52:53], 0
	v_mov_b64_e32 v[54:55], 0
	v_mov_b64_e32 v[56:57], 0
	v_mov_b64_e32 v[58:59], 0
	v_mov_b64_e32 v[60:61], 0
	v_mov_b64_e32 v[62:63], 0
	v_mov_b64_e32 v[64:65], 0
	v_mov_b64_e32 v[66:67], 0
	v_mov_b64_e32 v[68:69], 0
	v_mov_b64_e32 v[70:71], 0
	v_mov_b64_e32 v[72:73], 0
	v_mov_b64_e32 v[74:75], 0
	v_mov_b64_e32 v[76:77], 0
	v_mov_b64_e32 v[78:79], 0
	v_mov_b64_e32 v[80:81], 0
	v_mov_b64_e32 v[90:91], 0
	v_mov_b64_e32 v[92:93], 0
	v_mov_b64_e32 v[94:95], 0
	v_mov_b64_e32 v[96:97], 0
	v_mov_b64_e32 v[106:107], 0
	v_mov_b64_e32 v[108:109], 0
	v_mov_b64_e32 v[110:111], 0
	v_mov_b64_e32 v[112:113], 0
	v_mov_b64_e32 v[114:115], 0
	v_mov_b64_e32 v[116:117], 0
	v_mov_b64_e32 v[118:119], 0
	v_mov_b64_e32 v[120:121], 0
	v_mov_b64_e32 v[122:123], 0
	v_mov_b64_e32 v[124:125], 0
	v_mov_b64_e32 v[126:127], 0
	v_mov_b64_e32 v[128:129], 0
	v_mov_b64_e32 v[130:131], 0
	v_mov_b64_e32 v[132:133], 0
	v_mov_b64_e32 v[134:135], 0
	v_mov_b64_e32 v[136:137], 0
	v_mov_b64_e32 v[138:139], 0
	v_mov_b64_e32 v[140:141], 0
	v_mov_b64_e32 v[142:143], 0
	v_mov_b64_e32 v[144:145], 0
